# RGG epilogue: 1-a / b row stores of the two column halves paired into dwordx4 stores via v_permlane16_swap (using MFMA temporaries dead in the epilogue)
# speedup vs baseline: 1.0120x; 1.0041x over previous
.LBB0_1219:
	s_andn2_b64 vcc, exec, s[0:1]
	s_cbranch_vccnz .LBB0_1230
	s_add_i32 s0, s91, 0x20068
	v_mov_b32_e32 v0, s0
	ds_read_b32 v0, v0
	s_add_i32 s1, s91, 0x2006c
	s_add_i32 s2, s91, 0x20078
	s_add_i32 s3, s91, 0x2007c
	v_readlane_b32 s4, v254, 20
	s_waitcnt lgkmcnt(0)
	v_readfirstlane_b32 s0, v0
	v_mov_b32_e32 v0, s1
	ds_read_b32 v0, v0
	s_cmpk_gt_i32 s4, 0x41ff
	v_readlane_b32 s5, v254, 21
	s_waitcnt lgkmcnt(0)
	v_readfirstlane_b32 s1, v0
	v_mov_b32_e32 v0, s2
	ds_read_b32 v0, v0
	s_waitcnt lgkmcnt(0)
	v_readfirstlane_b32 s2, v0
	v_mov_b32_e32 v0, s3
	ds_read_b32 v0, v0
	s_waitcnt lgkmcnt(0)
	v_readfirstlane_b32 s3, v0
	s_cbranch_scc1 .LBB0_1230
	v_readlane_b32 s4, v254, 26
	s_lshl_b32 s4, s4, 13
	s_add_u32 s20, s0, s4
	s_addc_u32 s21, s1, 0
	s_add_u32 s22, s2, s4
	s_addc_u32 s23, s3, 0
	v_readlane_b32 s8, v254, 32
	s_mov_b32 s34, s24
	v_readlane_b32 s9, v254, 33
	s_add_u32 s24, s8, 0x15d08000
	s_addc_u32 s25, s9, 0
	s_add_u32 s0, s8, 0x8400000
	s_addc_u32 s1, s9, 0
	s_lshl_b32 s2, s81, 14
	v_readlane_b32 s6, v254, 20
	s_add_i32 s26, s91, s2
	s_ashr_i32 s2, s6, 31
	s_lshr_b32 s2, s2, 26
	s_add_i32 s2, s6, s2
	s_and_b32 s3, s2, 0xffffffc0
	s_sub_i32 s4, s6, s3
	s_lshr_b32 s2, s4, 1
	s_bfe_i32 s5, s2, 0x80000
	s_bfe_u32 s5, s5, 0x4000b
	s_add_i32 s5, s2, s5
	s_and_b32 s5, s5, 0xf0
	s_sub_i32 s2, s2, s5
	s_sext_i32_i8 s2, s2
	v_and_b32_e32 v135, 15, v162
	s_lshl_b32 s2, s2, 6
	v_or_b32_e32 v0, s3, v135
	s_ashr_i32 s3, s2, 31
	s_lshl_b64 s[2:3], s[2:3], 1
	s_add_u32 s2, s0, s2
	v_or_b32_e32 v10, 16, v0
	s_addc_u32 s3, s1, s3
	v_and_b32_e32 v152, 48, v164
	v_ashrrev_i32_e32 v11, 31, v10
	v_lshl_add_u64 v[2:3], s[2:3], 0, v[152:153]
	v_ashrrev_i32_e32 v1, 31, v0
	v_lshlrev_b64 v[10:11], 11, v[10:11]
	v_lshlrev_b64 v[8:9], 11, v[0:1]
	v_lshl_add_u64 v[12:13], v[2:3], 0, v[10:11]
	v_or_b32_e32 v10, 32, v0
	v_or_b32_e32 v0, 48, v0
	v_ashrrev_i32_e32 v1, 31, v0
	v_lshl_or_b32 v4, s4, 6, v135
	v_lshlrev_b64 v[0:1], 11, v[0:1]
	v_lshl_add_u64 v[28:29], v[2:3], 0, v[0:1]
	v_or_b32_e32 v0, 16, v4
	v_lshl_add_u64 v[6:7], s[8:9], 0, v[152:153]
	s_mov_b64 s[2:3], 0x14900000
	v_ashrrev_i32_e32 v1, 31, v0
	v_lshl_add_u64 v[132:133], v[6:7], 0, s[2:3]
	v_lshlrev_b64 v[0:1], 7, v[0:1]
	v_lshl_add_u64 v[44:45], v[132:133], 0, v[0:1]
	v_or_b32_e32 v0, 32, v4
	v_ashrrev_i32_e32 v1, 31, v0
	v_lshlrev_b64 v[0:1], 7, v[0:1]
	v_lshl_add_u64 v[52:53], v[132:133], 0, v[0:1]
	v_or_b32_e32 v0, 48, v4
	v_ashrrev_i32_e32 v5, 31, v4
	v_ashrrev_i32_e32 v11, 31, v10
	v_ashrrev_i32_e32 v1, 31, v0
	v_lshlrev_b64 v[6:7], 7, v[4:5]
	v_lshlrev_b64 v[10:11], 11, v[10:11]
	v_lshlrev_b64 v[0:1], 7, v[0:1]
	v_lshl_add_u64 v[8:9], v[2:3], 0, v[8:9]
	v_lshl_add_u64 v[20:21], v[2:3], 0, v[10:11]
	v_lshl_add_u64 v[36:37], v[132:133], 0, v[6:7]
	v_lshl_add_u64 v[60:61], v[132:133], 0, v[0:1]
	global_load_dwordx4 v[0:3], v[8:9], off
	global_load_dwordx4 v[4:7], v[8:9], off offset:64
	s_nop 0
	global_load_dwordx4 v[8:11], v[12:13], off
	s_nop 0
	global_load_dwordx4 v[12:15], v[12:13], off offset:64
	s_nop 0
	global_load_dwordx4 v[16:19], v[20:21], off
	s_nop 0
	global_load_dwordx4 v[20:23], v[20:21], off offset:64
	s_nop 0
	global_load_dwordx4 v[24:27], v[28:29], off
	s_nop 0
	global_load_dwordx4 v[28:31], v[28:29], off offset:64
	s_nop 0
	global_load_dwordx4 v[32:35], v[36:37], off
	s_nop 0
	global_load_dwordx4 v[36:39], v[36:37], off offset:64
	s_nop 0
	global_load_dwordx4 v[40:43], v[44:45], off
	s_nop 0
	global_load_dwordx4 v[44:47], v[44:45], off offset:64
	s_nop 0
	global_load_dwordx4 v[48:51], v[52:53], off
	s_nop 0
	global_load_dwordx4 v[52:55], v[52:53], off offset:64
	s_nop 0
	global_load_dwordx4 v[56:59], v[60:61], off
	s_nop 0
	global_load_dwordx4 v[60:63], v[60:61], off offset:64
	v_lshrrev_b32_e32 v64, 2, v164
	v_and_b32_e32 v134, 12, v64
	v_bitop3_b32 v157, v64, v135, 12 bitop3:0x6c
	v_bitop3_b32 v159, v134, v135, 1 bitop3:0x36
	v_bitop3_b32 v161, v134, v135, 2 bitop3:0x36
	v_bitop3_b32 v163, v134, v135, 3 bitop3:0x36
	v_bitop3_b32 v182, v134, v135, 16 bitop3:0x36
	v_bitop3_b32 v183, v134, v135, 17 bitop3:0x36
	v_bitop3_b32 v184, v134, v135, 18 bitop3:0x36
	v_bitop3_b32 v185, v134, v135, 19 bitop3:0x36
	v_lshl_add_u32 v64, v135, 8, s26
	v_lshl_add_u64 v[136:137], s[0:1], 0, v[152:153]
	v_lshl_add_u32 v186, v157, 3, v64
	v_lshl_add_u32 v187, v159, 3, v64
	v_lshl_add_u32 v188, v161, 3, v64
	v_lshl_add_u32 v189, v163, 3, v64
	v_lshl_add_u32 v190, v182, 3, v64
	v_lshl_add_u32 v191, v183, 3, v64
	v_lshl_add_u32 v192, v184, 3, v64
	v_lshl_add_u32 v193, v185, 3, v64
	v_cmp_gt_u32_e64 s[4:5], 32, v164
	v_lshlrev_b32_e32 v152, 1, v134
	v_lshlrev_b32_e32 v194, 3, v164
	s_mov_b32 s27, s6
	v_readlane_b32 s7, v254, 21
	v_mbcnt_lo_u32_b32 v160, -1, 0
	v_mbcnt_hi_u32_b32 v160, -1, v160
	v_and_b32_e32 v160, 16, v160
	v_lshrrev_b32_e32 v225, 1, v160
	v_add_u32_e32 v160, v160, v225
	s_waitcnt vmcnt(0)
	s_branch .LBB0_1223

.LBB0_1223:
	s_ashr_i32 s2, s27, 31
	s_waitcnt vmcnt(8)
	v_mfma_f32_16x16x32_bf16 v[64:67], v[32:35], v[0:3], 0
	s_lshr_b32 s2, s2, 26
	s_add_i32 s31, s27, s2
	s_and_b32 s2, s31, 0xffffffc0
	s_sub_i32 s30, s27, s2
	v_mfma_f32_16x16x32_bf16 v[124:127], v[36:39], v[4:7], v[64:67]
	s_nop 2
	v_or_b32_e32 v64, s2, v135
	s_lshl_b32 s2, s30, 5
	s_and_b32 s29, s2, 0x3c0
	v_mfma_f32_16x16x32_bf16 v[80:83], v[32:35], v[8:11], 0
	s_and_b32 s28, s2, 32
	s_lshl_b32 s3, s29, 1
	s_add_u32 s3, s0, s3
	v_mfma_f32_16x16x32_bf16 v[142:145], v[40:43], v[16:19], 0
	s_addc_u32 s7, s1, 0
	s_lshl_b32 s6, s28, 1
	s_add_u32 s6, s3, s6
	v_mfma_f32_16x16x32_bf16 v[88:91], v[48:51], v[8:11], 0
	v_ashrrev_i32_e32 v65, 31, v64
	v_or_b32_e32 v150, 16, v64
	s_addc_u32 s7, s7, 0
	v_mfma_f32_16x16x32_bf16 v[138:141], v[32:35], v[16:19], 0
	v_lshlrev_b64 v[130:131], 11, v[64:65]
	v_ashrrev_i32_e32 v151, 31, v150
	v_lshl_add_u64 v[66:67], s[6:7], 0, v[130:131]
	v_mfma_f32_16x16x32_bf16 v[68:71], v[40:43], v[0:3], 0
	v_lshlrev_b64 v[172:173], 11, v[150:151]
	v_lshl_add_u64 v[66:67], v[66:67], 0, v[152:153]
	v_mfma_f32_16x16x32_bf16 v[104:107], v[36:39], v[12:15], v[80:83]
	v_mfma_f32_16x16x32_bf16 v[80:83], v[44:47], v[20:23], v[142:145]
	s_nop 2
	v_or_b32_e32 v142, 32, v64
	v_mfma_f32_16x16x32_bf16 v[92:95], v[56:59], v[8:11], 0
	v_ashrrev_i32_e32 v143, 31, v142
	v_lshlrev_b64 v[166:167], 11, v[142:143]
	v_mfma_f32_16x16x32_bf16 v[146:149], v[48:51], v[16:19], 0
	v_mfma_f32_16x16x32_bf16 v[108:111], v[52:55], v[12:15], v[88:91]
	v_mfma_f32_16x16x32_bf16 v[88:91], v[36:39], v[20:23], v[138:141]
	s_nop 2
	v_or_b32_e32 v140, 48, v64
	v_mfma_f32_16x16x32_bf16 v[112:115], v[44:47], v[4:7], v[68:71]
	v_ashrrev_i32_e32 v141, 31, v140
	v_lshlrev_b64 v[144:145], 11, v[140:141]
	v_lshl_add_u64 v[64:65], s[6:7], 0, v[144:145]
	v_lshl_add_u64 v[68:69], s[6:7], 0, v[172:173]
	v_lshl_add_u64 v[68:69], v[68:69], 0, v[152:153]
	global_load_dwordx2 v[128:129], v[66:67], off
	global_load_dwordx2 v[176:177], v[66:67], off offset:32
	global_load_dwordx2 v[174:175], v[68:69], off
	global_load_dwordx2 v[170:171], v[68:69], off offset:32
	v_lshl_add_u64 v[66:67], s[6:7], 0, v[166:167]
	v_lshl_add_u64 v[66:67], v[66:67], 0, v[152:153]
	v_mfma_f32_16x16x32_bf16 v[100:103], v[60:63], v[12:15], v[92:95]
	v_lshl_add_u64 v[64:65], v[64:65], 0, v[152:153]
	v_readlane_b32 s6, v254, 22
	s_add_i32 s27, s27, s6
	v_mfma_f32_16x16x32_bf16 v[92:95], v[52:55], v[20:23], v[146:149]
	global_load_dwordx2 v[168:169], v[66:67], off
	s_nop 1
	global_load_dwordx2 v[148:149], v[66:67], off offset:32
	global_load_dwordx2 v[146:147], v[64:65], off
	global_load_dwordx2 v[138:139], v[64:65], off offset:32
	s_and_b32 s12, s2, 0x3e0
	s_and_b32 s14, s2, 0xfffffc00
	s_ashr_i32 s15, s14, 31
	s_lshl_b64 s[14:15], s[14:15], 2
	v_or_b32_e32 v224, s12, v134
	v_lshlrev_b32_e32 v224, 2, v224
	s_add_u32 s16, s20, s14
	s_addc_u32 s17, s21, s15
	global_load_dwordx4 v[212:215], v224, s[16:17]
	global_load_dwordx4 v[230:233], v224, s[16:17] offset:64
	s_add_u32 s16, s22, s14
	s_addc_u32 s17, s23, s15
	global_load_dwordx4 v[216:219], v224, s[16:17]
	global_load_dwordx4 v[234:237], v224, s[16:17] offset:64
	s_add_u32 s16, s24, s14
	s_addc_u32 s17, s25, s15
	global_load_dwordx4 v[220:223], v224, s[16:17]
	global_load_dwordx4 v[244:247], v224, s[16:17] offset:64
	v_readlane_b32 s7, v254, 23
	s_cmpk_gt_i32 s27, 0x41ff
	v_mfma_f32_16x16x32_bf16 v[72:75], v[48:51], v[0:3], 0
	s_cselect_b64 s[6:7], -1, 0
	s_and_b64 vcc, exec, s[6:7]
	v_mfma_f32_16x16x32_bf16 v[76:79], v[56:59], v[0:3], 0
	v_mfma_f32_16x16x32_bf16 v[84:87], v[40:43], v[8:11], 0
	v_mfma_f32_16x16x32_bf16 v[178:181], v[56:59], v[16:19], 0
	v_mfma_f32_16x16x32_bf16 v[196:199], v[32:35], v[24:27], 0
	v_mfma_f32_16x16x32_bf16 v[200:203], v[40:43], v[24:27], 0
	v_mfma_f32_16x16x32_bf16 v[204:207], v[48:51], v[24:27], 0
	v_mfma_f32_16x16x32_bf16 v[208:211], v[56:59], v[24:27], 0
	v_mfma_f32_16x16x32_bf16 v[120:123], v[52:55], v[4:7], v[72:75]
	v_mfma_f32_16x16x32_bf16 v[116:119], v[60:63], v[4:7], v[76:79]
	v_mfma_f32_16x16x32_bf16 v[96:99], v[44:47], v[12:15], v[84:87]
	v_mfma_f32_16x16x32_bf16 v[84:87], v[60:63], v[20:23], v[178:181]
	v_mfma_f32_16x16x32_bf16 v[72:75], v[36:39], v[28:31], v[196:199]
	v_mfma_f32_16x16x32_bf16 v[68:71], v[44:47], v[28:31], v[200:203]
	v_mfma_f32_16x16x32_bf16 v[76:79], v[52:55], v[28:31], v[204:207]
	v_mfma_f32_16x16x32_bf16 v[64:67], v[60:63], v[28:31], v[208:211]
	s_cbranch_vccnz .Lrg_nopf
	s_ashr_i32 s3, s27, 31
	s_lshr_b32 s3, s3, 26
	s_add_i32 s3, s27, s3
	s_andn2_b32 s3, s3, 63
	s_sub_i32 s10, s27, s3
	s_lshr_b32 s8, s10, 1
	s_bfe_i32 s9, s8, 0x80000
	s_bfe_u32 s9, s9, 0x4000b
	s_add_i32 s9, s8, s9
	s_and_b32 s9, s9, 0xf0
	s_sub_i32 s8, s8, s9
	s_sext_i32_i8 s8, s8
	v_or_b32_e32 v0, s3, v135
	s_lshl_b32 s8, s8, 6
	v_or_b32_e32 v10, 16, v0
	s_ashr_i32 s9, s8, 31
	v_ashrrev_i32_e32 v11, 31, v10
	v_lshl_add_u64 v[2:3], s[8:9], 1, v[136:137]
	v_ashrrev_i32_e32 v1, 31, v0
	v_lshlrev_b64 v[10:11], 11, v[10:11]
	v_lshlrev_b64 v[8:9], 11, v[0:1]
	v_lshl_add_u64 v[12:13], v[2:3], 0, v[10:11]
	v_or_b32_e32 v10, 32, v0
	v_or_b32_e32 v0, 48, v0
	v_ashrrev_i32_e32 v1, 31, v0
	v_lshl_or_b32 v4, s10, 6, v135
	v_lshlrev_b64 v[0:1], 11, v[0:1]
	v_lshl_add_u64 v[28:29], v[2:3], 0, v[0:1]
	v_or_b32_e32 v0, 16, v4
	v_ashrrev_i32_e32 v1, 31, v0
	v_lshlrev_b64 v[0:1], 7, v[0:1]
	v_lshl_add_u64 v[44:45], v[132:133], 0, v[0:1]
	v_or_b32_e32 v0, 32, v4
	v_ashrrev_i32_e32 v1, 31, v0
	v_lshlrev_b64 v[0:1], 7, v[0:1]
	v_lshl_add_u64 v[52:53], v[132:133], 0, v[0:1]
	v_or_b32_e32 v0, 48, v4
	v_ashrrev_i32_e32 v5, 31, v4
	v_ashrrev_i32_e32 v11, 31, v10
	v_ashrrev_i32_e32 v1, 31, v0
	v_lshlrev_b64 v[6:7], 7, v[4:5]
	v_lshlrev_b64 v[10:11], 11, v[10:11]
	v_lshlrev_b64 v[0:1], 7, v[0:1]
	v_lshl_add_u64 v[8:9], v[2:3], 0, v[8:9]
	v_lshl_add_u64 v[20:21], v[2:3], 0, v[10:11]
	v_lshl_add_u64 v[36:37], v[132:133], 0, v[6:7]
	v_lshl_add_u64 v[60:61], v[132:133], 0, v[0:1]
	global_load_dwordx4 v[0:3], v[8:9], off
	global_load_dwordx4 v[4:7], v[8:9], off offset:64
	s_nop 0
	global_load_dwordx4 v[8:11], v[12:13], off
	s_nop 0
	global_load_dwordx4 v[12:15], v[12:13], off offset:64
	s_nop 0
	global_load_dwordx4 v[16:19], v[20:21], off
	s_nop 0
	global_load_dwordx4 v[20:23], v[20:21], off offset:64
	s_nop 0
	global_load_dwordx4 v[24:27], v[28:29], off
	s_nop 0
	global_load_dwordx4 v[28:31], v[28:29], off offset:64
	s_nop 0
	global_load_dwordx4 v[32:35], v[36:37], off
	s_nop 0
	global_load_dwordx4 v[36:39], v[36:37], off offset:64
	s_nop 0
	global_load_dwordx4 v[40:43], v[44:45], off
	s_nop 0
	global_load_dwordx4 v[44:47], v[44:45], off offset:64
	s_nop 0
	global_load_dwordx4 v[48:51], v[52:53], off
	s_nop 0
	global_load_dwordx4 v[52:55], v[52:53], off offset:64
	s_nop 0
	global_load_dwordx4 v[56:59], v[60:61], off
	s_nop 0
	global_load_dwordx4 v[60:63], v[60:61], off offset:64
	s_waitcnt vmcnt(16)
	s_branch .LBB0_1225

.LBB0_1225:
	s_and_b32 s12, s2, 0x3e0
	s_and_b32 s2, s2, 0xfffffc00
	s_ashr_i32 s3, s2, 31
	s_cmp_lt_u32 s30, 32
	s_cselect_b64 s[8:9], -1, 0
	s_and_b64 s[10:11], s[8:9], exec
	s_mov_b32 s10, 0x4200000
	v_readlane_b32 s11, v254, 26
	s_cselect_b32 s10, 0xc600000, s10
	v_or_b32_e32 v143, s12, v134
	s_mul_i32 s11, s11, 0x10800000
	v_readlane_b32 s12, v254, 32
	s_cselect_b32 s11, 0xe700000, s11
	v_readlane_b32 s13, v254, 33
	s_add_u32 s18, s12, s10
	s_addc_u32 s19, s13, 0
	s_add_u32 s16, s12, s11
	s_addc_u32 s17, s13, 0
	s_lshl_b64 s[2:3], s[2:3], 2
	s_add_u32 s14, s20, s2
	s_addc_u32 s15, s21, s3
	v_lshlrev_b32_e32 v141, 2, v143
	s_add_u32 s12, s22, s2
	s_addc_u32 s13, s23, s3
	s_add_u32 s10, s24, s2
	s_addc_u32 s11, s25, s3
	v_lshlrev_b32_e32 v151, 16, v128
	v_and_b32_e32 v178, 0xffff0000, v129
	v_lshlrev_b32_e32 v143, 1, v143
	v_or_b32_e32 v130, v130, v143
	v_lshl_add_u64 v[180:181], s[18:19], 0, v[130:131]
	v_or_b32_e32 v172, v172, v143
	v_or_b32_e32 v166, v166, v143
	v_or_b32_e32 v144, v144, v143
	v_add_f32_e32 v124, v124, v212
	v_add_f32_e32 v125, v125, v213
	v_add_f32_e32 v126, v126, v214
	v_add_f32_e32 v127, v127, v215
	v_mul_f32_e32 v124, 0xbfb8aa3b, v124
	v_mul_f32_e32 v125, 0xbfb8aa3b, v125
	v_mul_f32_e32 v126, 0xbfb8aa3b, v126
	v_mul_f32_e32 v127, 0xbfb8aa3b, v127
	v_exp_f32_e32 v124, v124
	v_exp_f32_e32 v125, v125
	v_exp_f32_e32 v126, v126
	v_add_f32_e32 v120, v120, v216
	v_add_f32_e32 v121, v121, v217
	v_add_f32_e32 v122, v122, v218
	v_exp_f32_e32 v127, v127
	v_add_f32_e32 v123, v123, v219
	v_mul_f32_e32 v120, 0xbfb8aa3b, v120
	v_mul_f32_e32 v121, 0xbfb8aa3b, v121
	v_mul_f32_e32 v122, 0xbfb8aa3b, v122
	v_mul_f32_e32 v123, 0xbfb8aa3b, v123
	v_exp_f32_e32 v120, v120
	v_exp_f32_e32 v121, v121
	v_exp_f32_e32 v122, v122
	v_exp_f32_e32 v123, v123
	v_add_f32_e32 v124, 1.0, v124
	v_add_f32_e32 v125, 1.0, v125
	v_add_f32_e32 v126, 1.0, v126
	v_add_f32_e32 v127, 1.0, v127
	v_rcp_f32_e32 v124, v124
	v_rcp_f32_e32 v125, v125
	v_rcp_f32_e32 v126, v126
	v_rcp_f32_e32 v127, v127
	v_add_f32_e32 v120, 1.0, v120
	v_add_f32_e32 v121, 1.0, v121
	v_add_f32_e32 v122, 1.0, v122
	v_add_f32_e32 v123, 1.0, v123
	v_rcp_f32_e32 v179, v120
	v_rcp_f32_e32 v120, v121
	v_rcp_f32_e32 v121, v122
	v_rcp_f32_e32 v122, v123
	v_mul_f32_e64 v123, v124, -v220
	v_mul_f32_e64 v124, v125, -v221
	v_mul_f32_e64 v125, v126, -v222
	v_mul_f32_e64 v126, v127, -v223
	v_mul_f32_e32 v127, 0x3fb8aa3b, v123
	v_add_f32_e32 v123, v123, v123
	v_mul_f32_e32 v195, 0x3fb8aa3b, v124
	v_add_f32_e32 v124, v124, v124
	v_mul_f32_e32 v196, 0x3fb8aa3b, v125
	v_add_f32_e32 v125, v125, v125
	v_mul_f32_e32 v197, 0x3fb8aa3b, v126
	v_add_f32_e32 v126, v126, v126
	v_mul_f32_e32 v123, 0x3fb8aa3b, v123
	v_mul_f32_e32 v124, 0x3fb8aa3b, v124
	v_mul_f32_e32 v125, 0x3fb8aa3b, v125
	v_mul_f32_e32 v199, v179, v151
	v_exp_f32_e32 v179, v196
	v_mul_f32_e32 v196, 0x3fb8aa3b, v126
	v_mul_f32_e32 v126, v122, v178
	v_exp_f32_e32 v122, v123
	v_exp_f32_e32 v123, v124
	v_exp_f32_e32 v124, v125
	v_exp_f32_e32 v125, v196
	v_exp_f32_e32 v127, v127
	v_exp_f32_e32 v151, v195
	v_exp_f32_e32 v195, v197
	v_sub_f32_e32 v122, 1.0, v122
	v_sub_f32_e32 v123, 1.0, v123
	v_sub_f32_e32 v124, 1.0, v124
	v_sub_f32_e32 v125, 1.0, v125
	v_max_f32_e32 v122, 0, v122
	v_max_f32_e32 v123, 0, v123
	v_max_f32_e32 v124, 0, v124
	v_sub_f32_e32 v196, 1.0, v127
	v_sub_f32_e32 v197, 1.0, v151
	v_sub_f32_e32 v198, 1.0, v179
	v_sub_f32_e32 v151, 1.0, v195
	v_max_f32_e32 v125, 0, v125
	v_sqrt_f32_e32 v195, v122
	v_sqrt_f32_e32 v122, v123
	v_sqrt_f32_e32 v123, v124
	v_sqrt_f32_e32 v127, v125
	v_cvt_pk_f16_f32 v125, v198, v151
	v_cvt_pk_f16_f32 v124, v196, v197
	v_mov_b32_e32 v208, v124
	v_mov_b32_e32 v209, v125
	v_and_b32_e32 v124, 0xffff0000, v128
	v_lshlrev_b32_e32 v125, 16, v129
	v_pk_mul_f32 v[120:121], v[120:121], v[124:125]
	v_fma_mixlo_f16 v195, v199, v195, 0
	v_pk_mul_f32 v[120:121], v[120:121], v[122:123]
	v_fma_mixlo_f16 v200, v126, v127, 0
	v_cvt_pk_f16_f32 v199, v120, v121
	v_lshl_add_u64 v[178:179], s[16:17], 0, v[130:131]
	v_pack_b32_f16 v120, v195, v199
	v_alignbit_b32 v121, v200, v199, 16
	v_mov_b32_e32 v224, v120
	v_mov_b32_e32 v225, v121
	s_nop 0
	v_lshlrev_b32_e32 v201, 16, v176
	v_and_b32_e32 v202, 0xffff0000, v177
	v_and_b32_e32 v176, 0xffff0000, v176
	v_lshlrev_b32_e32 v177, 16, v177
	v_cvt_f16_f32_e32 v196, v196
	v_cvt_f16_f32_e32 v197, v197
	v_cvt_f16_f32_e32 v198, v198
	v_add_f32_e32 v112, v112, v230
	v_add_f32_e32 v116, v116, v234
	v_add_f32_e32 v113, v113, v231
	v_add_f32_e32 v114, v114, v232
	v_add_f32_e32 v117, v117, v235
	v_add_f32_e32 v115, v115, v233
	v_add_f32_e32 v119, v119, v237
	v_mul_f32_e32 v112, 0xbfb8aa3b, v112
	v_mul_f32_e32 v116, 0xbfb8aa3b, v116
	v_mul_f32_e32 v113, 0xbfb8aa3b, v113
	v_mul_f32_e32 v114, 0xbfb8aa3b, v114
	v_mul_f32_e32 v117, 0xbfb8aa3b, v117
	v_mul_f32_e32 v115, 0xbfb8aa3b, v115
	v_mul_f32_e32 v119, 0xbfb8aa3b, v119
	v_exp_f32_e32 v112, v112
	v_exp_f32_e32 v116, v116
	v_exp_f32_e32 v113, v113
	v_exp_f32_e32 v114, v114
	v_exp_f32_e32 v117, v117
	v_exp_f32_e32 v115, v115
	v_exp_f32_e32 v119, v119
	v_add_f32_e32 v118, v118, v236
	v_mul_f32_e32 v118, 0xbfb8aa3b, v118
	v_exp_f32_e32 v118, v118
	v_add_f32_e32 v112, 1.0, v112
	v_add_f32_e32 v116, 1.0, v116
	v_add_f32_e32 v113, 1.0, v113
	v_add_f32_e32 v114, 1.0, v114
	v_add_f32_e32 v117, 1.0, v117
	v_add_f32_e32 v115, 1.0, v115
	v_add_f32_e32 v119, 1.0, v119
	v_rcp_f32_e32 v124, v112
	v_rcp_f32_e32 v116, v116
	v_rcp_f32_e32 v125, v113
	v_rcp_f32_e32 v114, v114
	v_rcp_f32_e32 v112, v117
	v_rcp_f32_e32 v115, v115
	v_rcp_f32_e32 v117, v119
	v_add_f32_e32 v118, 1.0, v118
	v_rcp_f32_e32 v113, v118
	v_mul_f32_e64 v118, v124, -v244
	v_mul_f32_e32 v119, v116, v201
	v_mul_f32_e64 v116, v125, -v245
	v_mul_f32_e64 v114, v114, -v246
	v_mul_f32_e64 v115, v115, -v247
	v_mul_f32_e32 v120, v117, v202
	v_mul_f32_e32 v117, 0x3fb8aa3b, v118
	v_add_f32_e32 v118, v118, v118
	v_mul_f32_e32 v121, 0x3fb8aa3b, v116
	v_add_f32_e32 v116, v116, v116
	v_mul_f32_e32 v122, 0x3fb8aa3b, v114
	v_add_f32_e32 v114, v114, v114
	v_mul_f32_e32 v123, 0x3fb8aa3b, v115
	v_add_f32_e32 v115, v115, v115
	v_mul_f32_e32 v118, 0x3fb8aa3b, v118
	v_mul_f32_e32 v116, 0x3fb8aa3b, v116
	v_mul_f32_e32 v114, 0x3fb8aa3b, v114
	v_exp_f32_e32 v117, v117
	v_mul_f32_e32 v115, 0x3fb8aa3b, v115
	v_exp_f32_e32 v118, v118
	v_exp_f32_e32 v116, v116
	v_exp_f32_e32 v114, v114
	v_exp_f32_e32 v121, v121
	v_exp_f32_e32 v115, v115
	v_exp_f32_e32 v122, v122
	v_sub_f32_e32 v128, 1.0, v117
	v_sub_f32_e32 v117, 1.0, v118
	v_sub_f32_e32 v116, 1.0, v116
	v_sub_f32_e32 v118, 1.0, v114
	v_exp_f32_e32 v123, v123
	v_sub_f32_e32 v129, 1.0, v121
	v_sub_f32_e32 v121, 1.0, v115
	v_max_f32_e32 v117, 0, v117
	v_max_f32_e32 v116, 0, v116
	v_max_f32_e32 v118, 0, v118
	v_sub_f32_e32 v130, 1.0, v122
	v_max_f32_e32 v121, 0, v121
	v_sqrt_f32_e32 v122, v117
	v_sqrt_f32_e32 v116, v116
	v_sqrt_f32_e32 v117, v118
	v_sqrt_f32_e32 v118, v121
	v_pk_mul_f32 v[112:113], v[112:113], v[176:177]
	v_sub_f32_e32 v131, 1.0, v123
	v_cvt_pk_f16_f32 v115, v130, v131
	v_cvt_pk_f16_f32 v114, v128, v129
	v_pk_mul_f32 v[112:113], v[112:113], v[116:117]
	v_mov_b32_e32 v210, v114
	v_mov_b32_e32 v211, v115
	v_add_u32_e32 v180, v160, v180
	s_nop 0
	v_permlane16_swap_b32 v208, v210
	v_permlane16_swap_b32 v209, v211
	global_store_dwordx4 v[180:181], v[208:211], off
	v_fma_mixlo_f16 v176, v119, v122, 0
	v_fma_mixlo_f16 v180, v120, v118, 0
	v_cvt_pk_f16_f32 v177, v112, v113
	v_pack_b32_f16 v112, v176, v177
	v_alignbit_b32 v113, v180, v177, 16
	v_add_u32_e32 v178, v160, v178
	s_nop 1
	v_mov_b32_e32 v208, v224
	v_mov_b32_e32 v209, v225
	v_mov_b32_e32 v210, v112
	v_mov_b32_e32 v211, v113
	s_nop 1
	v_permlane16_swap_b32 v208, v210
	v_permlane16_swap_b32 v209, v211
	global_store_dwordx4 v[178:179], v[208:211], off
	s_nop 0
	v_lshlrev_b32_e32 v178, 16, v174
	v_and_b32_e32 v179, 0xffff0000, v175
	v_and_b32_e32 v174, 0xffff0000, v174
	v_lshlrev_b32_e32 v175, 16, v175
	v_lshl_add_u64 v[126:127], s[18:19], 0, v[172:173]
	v_lshl_add_u64 v[124:125], s[16:17], 0, v[172:173]
	v_and_b32_e32 v172, 0xffff0000, v171
	v_lshlrev_b32_e32 v171, 16, v171
	v_add_f32_e32 v104, v104, v212
	v_add_f32_e32 v108, v108, v216
	v_add_f32_e32 v105, v105, v213
	v_add_f32_e32 v106, v106, v214
	v_add_f32_e32 v109, v109, v217
	v_add_f32_e32 v107, v107, v215
	v_add_f32_e32 v111, v111, v219
	v_mul_f32_e32 v104, 0xbfb8aa3b, v104
	v_mul_f32_e32 v108, 0xbfb8aa3b, v108
	v_mul_f32_e32 v105, 0xbfb8aa3b, v105
	v_mul_f32_e32 v106, 0xbfb8aa3b, v106
	v_mul_f32_e32 v109, 0xbfb8aa3b, v109
	v_mul_f32_e32 v107, 0xbfb8aa3b, v107
	v_mul_f32_e32 v111, 0xbfb8aa3b, v111
	v_exp_f32_e32 v104, v104
	v_exp_f32_e32 v108, v108
	v_exp_f32_e32 v105, v105
	v_exp_f32_e32 v106, v106
	v_exp_f32_e32 v109, v109
	v_exp_f32_e32 v107, v107
	v_exp_f32_e32 v111, v111
	v_add_f32_e32 v110, v110, v218
	v_mul_f32_e32 v110, 0xbfb8aa3b, v110
	v_exp_f32_e32 v110, v110
	v_add_f32_e32 v104, 1.0, v104
	v_add_f32_e32 v108, 1.0, v108
	v_add_f32_e32 v105, 1.0, v105
	v_add_f32_e32 v106, 1.0, v106
	v_add_f32_e32 v109, 1.0, v109
	v_add_f32_e32 v107, 1.0, v107
	v_add_f32_e32 v111, 1.0, v111
	v_rcp_f32_e32 v116, v104
	v_rcp_f32_e32 v108, v108
	v_rcp_f32_e32 v117, v105
	v_rcp_f32_e32 v106, v106
	v_rcp_f32_e32 v104, v109
	v_rcp_f32_e32 v107, v107
	v_rcp_f32_e32 v109, v111
	v_add_f32_e32 v110, 1.0, v110
	v_rcp_f32_e32 v105, v110
	v_mul_f32_e64 v110, v116, -v220
	v_mul_f32_e32 v111, v108, v178
	v_mul_f32_e64 v108, v117, -v221
	v_mul_f32_e64 v106, v106, -v222
	v_mul_f32_e64 v107, v107, -v223
	v_mul_f32_e32 v112, v109, v179
	v_mul_f32_e32 v109, 0x3fb8aa3b, v110
	v_add_f32_e32 v110, v110, v110
	v_mul_f32_e32 v113, 0x3fb8aa3b, v108
	v_add_f32_e32 v108, v108, v108
	v_mul_f32_e32 v114, 0x3fb8aa3b, v106
	v_add_f32_e32 v106, v106, v106
	v_mul_f32_e32 v115, 0x3fb8aa3b, v107
	v_add_f32_e32 v107, v107, v107
	v_mul_f32_e32 v110, 0x3fb8aa3b, v110
	v_mul_f32_e32 v108, 0x3fb8aa3b, v108
	v_mul_f32_e32 v106, 0x3fb8aa3b, v106
	v_exp_f32_e32 v109, v109
	v_mul_f32_e32 v107, 0x3fb8aa3b, v107
	v_exp_f32_e32 v110, v110
	v_exp_f32_e32 v108, v108
	v_exp_f32_e32 v106, v106
	v_exp_f32_e32 v113, v113
	v_exp_f32_e32 v107, v107
	v_exp_f32_e32 v114, v114
	v_sub_f32_e32 v116, 1.0, v109
	v_sub_f32_e32 v109, 1.0, v110
	v_sub_f32_e32 v108, 1.0, v108
	v_sub_f32_e32 v110, 1.0, v106
	v_sub_f32_e32 v117, 1.0, v113
	v_sub_f32_e32 v113, 1.0, v107
	v_max_f32_e32 v109, 0, v109
	v_max_f32_e32 v108, 0, v108
	v_max_f32_e32 v110, 0, v110
	v_sub_f32_e32 v118, 1.0, v114
	v_max_f32_e32 v113, 0, v113
	v_sqrt_f32_e32 v114, v109
	v_sqrt_f32_e32 v108, v108
	v_sqrt_f32_e32 v109, v110
	v_exp_f32_e32 v115, v115
	v_sqrt_f32_e32 v110, v113
	v_pk_mul_f32 v[104:105], v[104:105], v[174:175]
	v_fma_mixlo_f16 v120, v111, v114, 0
	v_pk_mul_f32 v[104:105], v[104:105], v[108:109]
	v_sub_f32_e32 v119, 1.0, v115
	v_fma_mixlo_f16 v122, v112, v110, 0
	v_cvt_pk_f16_f32 v121, v104, v105
	v_cvt_pk_f16_f32 v107, v118, v119
	v_cvt_pk_f16_f32 v106, v116, v117
	v_pack_b32_f16 v104, v120, v121
	v_alignbit_b32 v105, v122, v121, 16
	v_mov_b32_e32 v208, v106
	v_mov_b32_e32 v209, v107
	v_mov_b32_e32 v224, v104
	v_mov_b32_e32 v225, v105
	s_nop 0
	v_lshlrev_b32_e32 v123, 16, v170
	v_and_b32_e32 v170, 0xffff0000, v170
	v_add_f32_e32 v96, v96, v230
	v_add_f32_e32 v100, v100, v234
	v_add_f32_e32 v97, v97, v231
	v_add_f32_e32 v98, v98, v232
	v_add_f32_e32 v101, v101, v235
	v_add_f32_e32 v99, v99, v233
	v_add_f32_e32 v103, v103, v237
	v_mul_f32_e32 v96, 0xbfb8aa3b, v96
	v_mul_f32_e32 v100, 0xbfb8aa3b, v100
	v_mul_f32_e32 v97, 0xbfb8aa3b, v97
	v_mul_f32_e32 v98, 0xbfb8aa3b, v98
	v_mul_f32_e32 v101, 0xbfb8aa3b, v101
	v_mul_f32_e32 v99, 0xbfb8aa3b, v99
	v_mul_f32_e32 v103, 0xbfb8aa3b, v103
	v_exp_f32_e32 v96, v96
	v_exp_f32_e32 v100, v100
	v_exp_f32_e32 v97, v97
	v_exp_f32_e32 v98, v98
	v_exp_f32_e32 v101, v101
	v_exp_f32_e32 v99, v99
	v_exp_f32_e32 v103, v103
	v_add_f32_e32 v102, v102, v236
	v_mul_f32_e32 v102, 0xbfb8aa3b, v102
	v_exp_f32_e32 v102, v102
	v_add_f32_e32 v96, 1.0, v96
	v_add_f32_e32 v100, 1.0, v100
	v_add_f32_e32 v97, 1.0, v97
	v_add_f32_e32 v98, 1.0, v98
	v_add_f32_e32 v101, 1.0, v101
	v_add_f32_e32 v99, 1.0, v99
	v_add_f32_e32 v103, 1.0, v103
	v_rcp_f32_e32 v108, v96
	v_rcp_f32_e32 v100, v100
	v_rcp_f32_e32 v109, v97
	v_rcp_f32_e32 v98, v98
	v_rcp_f32_e32 v96, v101
	v_rcp_f32_e32 v99, v99
	v_rcp_f32_e32 v101, v103
	v_add_f32_e32 v102, 1.0, v102
	v_rcp_f32_e32 v97, v102
	v_mul_f32_e64 v102, v108, -v244
	v_mul_f32_e32 v103, v100, v123
	v_mul_f32_e64 v100, v109, -v245
	v_mul_f32_e64 v98, v98, -v246
	v_mul_f32_e64 v99, v99, -v247
	v_mul_f32_e32 v104, v101, v172
	v_mul_f32_e32 v101, 0x3fb8aa3b, v102
	v_add_f32_e32 v102, v102, v102
	v_mul_f32_e32 v105, 0x3fb8aa3b, v100
	v_add_f32_e32 v100, v100, v100
	v_mul_f32_e32 v106, 0x3fb8aa3b, v98
	v_add_f32_e32 v98, v98, v98
	v_mul_f32_e32 v107, 0x3fb8aa3b, v99
	v_add_f32_e32 v99, v99, v99
	v_mul_f32_e32 v102, 0x3fb8aa3b, v102
	v_mul_f32_e32 v100, 0x3fb8aa3b, v100
	v_mul_f32_e32 v98, 0x3fb8aa3b, v98
	v_exp_f32_e32 v101, v101
	v_mul_f32_e32 v99, 0x3fb8aa3b, v99
	v_exp_f32_e32 v102, v102
	v_exp_f32_e32 v100, v100
	v_exp_f32_e32 v98, v98
	v_exp_f32_e32 v105, v105
	v_exp_f32_e32 v99, v99
	v_exp_f32_e32 v106, v106
	v_pk_mul_f32 v[96:97], v[96:97], v[170:171]
	v_sub_f32_e32 v170, 1.0, v101
	v_sub_f32_e32 v101, 1.0, v102
	v_sub_f32_e32 v100, 1.0, v100
	v_sub_f32_e32 v102, 1.0, v98
	v_exp_f32_e32 v107, v107
	v_sub_f32_e32 v171, 1.0, v105
	v_sub_f32_e32 v105, 1.0, v99
	v_max_f32_e32 v101, 0, v101
	v_max_f32_e32 v100, 0, v100
	v_max_f32_e32 v102, 0, v102
	v_sub_f32_e32 v172, 1.0, v106
	v_max_f32_e32 v105, 0, v105
	v_sqrt_f32_e32 v106, v101
	v_sqrt_f32_e32 v100, v100
	v_sqrt_f32_e32 v101, v102
	v_sqrt_f32_e32 v102, v105
	v_sub_f32_e32 v173, 1.0, v107
	v_cvt_pk_f16_f32 v99, v172, v173
	v_cvt_pk_f16_f32 v98, v170, v171
	v_pk_mul_f32 v[96:97], v[96:97], v[100:101]
	v_mov_b32_e32 v210, v98
	v_mov_b32_e32 v211, v99
	v_add_u32_e32 v126, v160, v126
	s_nop 0
	v_permlane16_swap_b32 v208, v210
	v_permlane16_swap_b32 v209, v211
	global_store_dwordx4 v[126:127], v[208:211], off
	v_fma_mixlo_f16 v126, v103, v106, 0
	v_fma_mixlo_f16 v174, v104, v102, 0
	v_cvt_pk_f16_f32 v127, v96, v97
	v_pack_b32_f16 v96, v126, v127
	v_alignbit_b32 v97, v174, v127, 16
	v_add_u32_e32 v124, v160, v124
	s_nop 1
	v_mov_b32_e32 v208, v224
	v_mov_b32_e32 v209, v225
	v_mov_b32_e32 v210, v96
	v_mov_b32_e32 v211, v97
	s_nop 1
	v_permlane16_swap_b32 v208, v210
	v_permlane16_swap_b32 v209, v211
	global_store_dwordx4 v[124:125], v[208:211], off
	s_nop 0
	v_lshlrev_b32_e32 v114, 16, v168
	v_and_b32_e32 v115, 0xffff0000, v169
	v_lshl_add_u64 v[110:111], s[18:19], 0, v[166:167]
	v_lshl_add_u64 v[108:109], s[16:17], 0, v[166:167]
	v_and_b32_e32 v112, 0xffff0000, v168
	v_lshlrev_b32_e32 v113, 16, v169
	v_lshlrev_b32_e32 v167, 16, v148
	v_lshlrev_b32_e32 v125, 8, v150
	v_and_b32_e32 v150, 0xffff0000, v149
	v_and_b32_e32 v168, 0xffff0000, v148
	v_lshlrev_b32_e32 v169, 16, v149
	v_and_b32_e32 v125, 0x1f00, v125
	v_lshlrev_b32_e32 v124, 3, v157
	v_add_u32_e32 v125, s26, v125
	v_lshlrev_b32_e32 v123, 3, v159
	v_lshlrev_b32_e32 v149, 16, v146
	v_add_u32_e32 v175, v125, v124
	v_add_u32_e32 v178, v125, v123
	v_and_b32_e32 v148, 0xffff0000, v147
	v_add_f32_e32 v88, v88, v212
	v_add_f32_e32 v92, v92, v216
	v_add_f32_e32 v89, v89, v213
	v_add_f32_e32 v90, v90, v214
	v_add_f32_e32 v93, v93, v217
	v_add_f32_e32 v91, v91, v215
	v_add_f32_e32 v95, v95, v219
	v_mul_f32_e32 v88, 0xbfb8aa3b, v88
	v_mul_f32_e32 v92, 0xbfb8aa3b, v92
	v_mul_f32_e32 v89, 0xbfb8aa3b, v89
	v_mul_f32_e32 v90, 0xbfb8aa3b, v90
	v_mul_f32_e32 v93, 0xbfb8aa3b, v93
	v_mul_f32_e32 v91, 0xbfb8aa3b, v91
	v_mul_f32_e32 v95, 0xbfb8aa3b, v95
	v_exp_f32_e32 v88, v88
	v_exp_f32_e32 v92, v92
	v_exp_f32_e32 v89, v89
	v_exp_f32_e32 v90, v90
	v_exp_f32_e32 v93, v93
	v_exp_f32_e32 v91, v91
	v_exp_f32_e32 v95, v95
	v_add_f32_e32 v94, v94, v218
	v_mul_f32_e32 v94, 0xbfb8aa3b, v94
	v_exp_f32_e32 v94, v94
	v_add_f32_e32 v88, 1.0, v88
	v_add_f32_e32 v92, 1.0, v92
	v_add_f32_e32 v89, 1.0, v89
	v_add_f32_e32 v90, 1.0, v90
	v_add_f32_e32 v93, 1.0, v93
	v_add_f32_e32 v91, 1.0, v91
	v_add_f32_e32 v95, 1.0, v95
	v_rcp_f32_e32 v100, v88
	v_rcp_f32_e32 v92, v92
	v_rcp_f32_e32 v101, v89
	v_rcp_f32_e32 v90, v90
	v_rcp_f32_e32 v88, v93
	v_rcp_f32_e32 v91, v91
	v_rcp_f32_e32 v93, v95
	v_add_f32_e32 v94, 1.0, v94
	v_rcp_f32_e32 v89, v94
	v_mul_f32_e64 v94, v100, -v220
	v_mul_f32_e32 v95, v92, v114
	v_mul_f32_e64 v92, v101, -v221
	v_mul_f32_e64 v90, v90, -v222
	v_mul_f32_e64 v91, v91, -v223
	v_mul_f32_e32 v96, v93, v115
	v_mul_f32_e32 v93, 0x3fb8aa3b, v94
	v_add_f32_e32 v94, v94, v94
	v_mul_f32_e32 v97, 0x3fb8aa3b, v92
	v_add_f32_e32 v92, v92, v92
	v_mul_f32_e32 v98, 0x3fb8aa3b, v90
	v_add_f32_e32 v90, v90, v90
	v_mul_f32_e32 v99, 0x3fb8aa3b, v91
	v_add_f32_e32 v91, v91, v91
	v_mul_f32_e32 v94, 0x3fb8aa3b, v94
	v_mul_f32_e32 v92, 0x3fb8aa3b, v92
	v_mul_f32_e32 v90, 0x3fb8aa3b, v90
	v_exp_f32_e32 v93, v93
	v_mul_f32_e32 v91, 0x3fb8aa3b, v91
	v_exp_f32_e32 v94, v94
	v_exp_f32_e32 v92, v92
	v_exp_f32_e32 v90, v90
	v_exp_f32_e32 v97, v97
	v_exp_f32_e32 v91, v91
	v_exp_f32_e32 v98, v98
	v_sub_f32_e32 v166, 1.0, v93
	v_sub_f32_e32 v93, 1.0, v94
	v_sub_f32_e32 v92, 1.0, v92
	v_sub_f32_e32 v94, 1.0, v90
	v_sub_f32_e32 v104, 1.0, v97
	v_sub_f32_e32 v97, 1.0, v91
	v_max_f32_e32 v93, 0, v93
	v_max_f32_e32 v92, 0, v92
	v_max_f32_e32 v94, 0, v94
	v_sub_f32_e32 v105, 1.0, v98
	v_max_f32_e32 v97, 0, v97
	v_sqrt_f32_e32 v98, v93
	v_sqrt_f32_e32 v92, v92
	v_sqrt_f32_e32 v93, v94
	v_exp_f32_e32 v99, v99
	v_sqrt_f32_e32 v94, v97
	v_pk_mul_f32 v[88:89], v[88:89], v[112:113]
	v_fma_mixlo_f16 v107, v95, v98, 0
	v_pk_mul_f32 v[88:89], v[88:89], v[92:93]
	v_sub_f32_e32 v106, 1.0, v99
	v_fma_mixlo_f16 v112, v96, v94, 0
	v_cvt_pk_f16_f32 v113, v88, v89
	v_cvt_pk_f16_f32 v91, v105, v106
	v_cvt_pk_f16_f32 v90, v166, v104
	v_pack_b32_f16 v88, v107, v113
	v_alignbit_b32 v89, v112, v113, 16
	v_mov_b32_e32 v208, v90
	v_mov_b32_e32 v209, v91
	v_mov_b32_e32 v224, v88
	v_mov_b32_e32 v225, v89
	s_nop 0
	v_lshlrev_b32_e32 v115, 3, v161
	v_lshlrev_b32_e32 v114, 3, v163
	v_add_u32_e32 v179, v125, v115
	v_add_u32_e32 v181, v125, v114
	v_lshlrev_b32_e32 v103, 3, v182
	v_lshlrev_b32_e32 v102, 3, v183
	v_lshlrev_b32_e32 v101, 3, v184
	v_add_u32_e32 v201, v125, v103
	v_add_u32_e32 v202, v125, v102
	v_add_u32_e32 v203, v125, v101
	v_lshlrev_b32_e32 v100, 3, v185
	v_add_u32_e32 v125, v125, v100
	v_add_f32_e32 v80, v80, v230
	v_add_f32_e32 v84, v84, v234
	v_add_f32_e32 v81, v81, v231
	v_add_f32_e32 v82, v82, v232
	v_add_f32_e32 v85, v85, v235
	v_add_f32_e32 v83, v83, v233
	v_add_f32_e32 v87, v87, v237
	v_mul_f32_e32 v80, 0xbfb8aa3b, v80
	v_mul_f32_e32 v84, 0xbfb8aa3b, v84
	v_mul_f32_e32 v81, 0xbfb8aa3b, v81
	v_mul_f32_e32 v82, 0xbfb8aa3b, v82
	v_mul_f32_e32 v85, 0xbfb8aa3b, v85
	v_mul_f32_e32 v83, 0xbfb8aa3b, v83
	v_mul_f32_e32 v87, 0xbfb8aa3b, v87
	v_exp_f32_e32 v80, v80
	v_exp_f32_e32 v84, v84
	v_exp_f32_e32 v81, v81
	v_exp_f32_e32 v82, v82
	v_exp_f32_e32 v85, v85
	v_exp_f32_e32 v83, v83
	v_exp_f32_e32 v87, v87
	v_add_f32_e32 v86, v86, v236
	v_mul_f32_e32 v86, 0xbfb8aa3b, v86
	v_exp_f32_e32 v86, v86
	v_add_f32_e32 v80, 1.0, v80
	v_add_f32_e32 v84, 1.0, v84
	v_add_f32_e32 v81, 1.0, v81
	v_add_f32_e32 v82, 1.0, v82
	v_add_f32_e32 v85, 1.0, v85
	v_add_f32_e32 v83, 1.0, v83
	v_add_f32_e32 v87, 1.0, v87
	v_rcp_f32_e32 v92, v80
	v_rcp_f32_e32 v84, v84
	v_rcp_f32_e32 v93, v81
	v_rcp_f32_e32 v82, v82
	v_rcp_f32_e32 v80, v85
	v_rcp_f32_e32 v83, v83
	v_rcp_f32_e32 v85, v87
	v_add_f32_e32 v86, 1.0, v86
	v_rcp_f32_e32 v81, v86
	v_mul_f32_e64 v86, v92, -v244
	v_mul_f32_e32 v87, v84, v167
	v_mul_f32_e64 v84, v93, -v245
	v_mul_f32_e64 v82, v82, -v246
	v_mul_f32_e64 v83, v83, -v247
	v_mul_f32_e32 v88, v85, v150
	v_mul_f32_e32 v85, 0x3fb8aa3b, v86
	v_add_f32_e32 v86, v86, v86
	v_mul_f32_e32 v89, 0x3fb8aa3b, v84
	v_add_f32_e32 v84, v84, v84
	v_mul_f32_e32 v90, 0x3fb8aa3b, v82
	v_add_f32_e32 v82, v82, v82
	v_mul_f32_e32 v91, 0x3fb8aa3b, v83
	v_add_f32_e32 v83, v83, v83
	v_mul_f32_e32 v86, 0x3fb8aa3b, v86
	v_mul_f32_e32 v84, 0x3fb8aa3b, v84
	v_mul_f32_e32 v82, 0x3fb8aa3b, v82
	v_exp_f32_e32 v85, v85
	v_mul_f32_e32 v83, 0x3fb8aa3b, v83
	v_exp_f32_e32 v86, v86
	v_exp_f32_e32 v84, v84
	v_exp_f32_e32 v82, v82
	v_exp_f32_e32 v89, v89
	v_exp_f32_e32 v83, v83
	v_exp_f32_e32 v90, v90
	v_sub_f32_e32 v98, 1.0, v85
	v_sub_f32_e32 v85, 1.0, v86
	v_sub_f32_e32 v84, 1.0, v84
	v_sub_f32_e32 v86, 1.0, v82
	v_exp_f32_e32 v91, v91
	v_sub_f32_e32 v96, 1.0, v89
	v_sub_f32_e32 v89, 1.0, v83
	v_max_f32_e32 v85, 0, v85
	v_max_f32_e32 v84, 0, v84
	v_max_f32_e32 v86, 0, v86
	v_sub_f32_e32 v94, 1.0, v90
	v_max_f32_e32 v89, 0, v89
	v_sqrt_f32_e32 v90, v85
	v_sqrt_f32_e32 v84, v84
	v_sqrt_f32_e32 v85, v86
	v_sqrt_f32_e32 v86, v89
	v_pk_mul_f32 v[80:81], v[80:81], v[168:169]
	v_sub_f32_e32 v95, 1.0, v91
	v_cvt_pk_f16_f32 v83, v94, v95
	v_cvt_pk_f16_f32 v82, v98, v96
	v_pk_mul_f32 v[80:81], v[80:81], v[84:85]
	v_mov_b32_e32 v210, v82
	v_mov_b32_e32 v211, v83
	v_add_u32_e32 v110, v160, v110
	s_nop 0
	v_permlane16_swap_b32 v208, v210
	v_permlane16_swap_b32 v209, v211
	global_store_dwordx4 v[110:111], v[208:211], off
	v_fma_mixlo_f16 v110, v87, v90, 0
	v_fma_mixlo_f16 v97, v88, v86, 0
	v_cvt_pk_f16_f32 v99, v80, v81
	v_pack_b32_f16 v80, v110, v99
	v_alignbit_b32 v81, v97, v99, 16
	v_add_u32_e32 v108, v160, v108
	s_nop 1
	v_mov_b32_e32 v208, v224
	v_mov_b32_e32 v209, v225
	v_mov_b32_e32 v210, v80
	v_mov_b32_e32 v211, v81
	s_nop 1
	v_permlane16_swap_b32 v208, v210
	v_permlane16_swap_b32 v209, v211
	global_store_dwordx4 v[108:109], v[208:211], off
	s_nop 0
	v_cvt_f16_f32_e32 v84, v151
	v_cvt_f32_f16_e32 v85, v196
	v_cvt_f32_f16_e32 v86, v197
	v_cvt_f32_f16_e32 v108, v198
	v_cvt_f32_f16_e32 v111, v84
	v_sub_f32_e32 v92, 1.0, v85
	v_sub_f32_e32 v150, 1.0, v86
	v_cvt_f32_f16_e32 v93, v195
	v_cvt_f32_f16_e32 v151, v199
	v_cvt_f32_f16_sdwa v169, v199 dst_sel:DWORD dst_unused:UNUSED_PAD src0_sel:WORD_1
	v_cvt_f32_f16_e32 v109, v200
	v_sub_f32_e32 v168, 1.0, v108
	v_sub_f32_e32 v108, 1.0, v111
	ds_write_b64 v186, v[92:93]
	ds_write_b64 v187, v[150:151]
	ds_write_b64 v188, v[168:169]
	ds_write_b64 v189, v[108:109]
	v_cvt_f16_f32_e32 v92, v128
	v_cvt_f16_f32_e32 v93, v129
	v_cvt_f16_f32_e32 v108, v130
	v_cvt_f16_f32_e32 v109, v131
	v_cvt_f32_f16_e32 v92, v92
	v_cvt_f32_f16_e32 v111, v93
	v_cvt_f32_f16_e32 v108, v108
	v_cvt_f32_f16_e32 v150, v109
	v_cvt_f32_f16_e32 v93, v176
	v_cvt_f32_f16_e32 v129, v177
	v_cvt_f32_f16_sdwa v131, v177 dst_sel:DWORD dst_unused:UNUSED_PAD src0_sel:WORD_1
	v_cvt_f32_f16_e32 v109, v180
	v_sub_f32_e32 v92, 1.0, v92
	v_sub_f32_e32 v128, 1.0, v111
	v_sub_f32_e32 v130, 1.0, v108
	v_sub_f32_e32 v108, 1.0, v150
	ds_write_b64 v190, v[92:93]
	ds_write_b64 v191, v[128:129]
	ds_write_b64 v192, v[130:131]
	ds_write_b64 v193, v[108:109]
	v_cvt_f16_f32_e32 v92, v116
	v_cvt_f16_f32_e32 v93, v117
	v_cvt_f16_f32_e32 v108, v118
	v_cvt_f16_f32_e32 v109, v119
	v_cvt_f32_f16_e32 v92, v92
	v_cvt_f32_f16_e32 v111, v93
	v_cvt_f32_f16_e32 v108, v108
	v_cvt_f32_f16_e32 v128, v109
	v_cvt_f32_f16_e32 v93, v120
	v_cvt_f32_f16_e32 v117, v121
	v_cvt_f32_f16_sdwa v119, v121 dst_sel:DWORD dst_unused:UNUSED_PAD src0_sel:WORD_1
	v_cvt_f32_f16_e32 v109, v122
	v_sub_f32_e32 v92, 1.0, v92
	v_sub_f32_e32 v116, 1.0, v111
	v_sub_f32_e32 v118, 1.0, v108
	v_sub_f32_e32 v108, 1.0, v128
	ds_write_b64 v175, v[92:93]
	ds_write_b64 v178, v[116:117]
	ds_write_b64 v179, v[118:119]
	ds_write_b64 v181, v[108:109]
	v_cvt_f16_f32_e32 v92, v170
	v_cvt_f16_f32_e32 v93, v171
	v_cvt_f16_f32_e32 v108, v172
	v_cvt_f16_f32_e32 v109, v173
	v_cvt_f32_f16_e32 v92, v92
	v_cvt_f32_f16_e32 v111, v93
	v_cvt_f32_f16_e32 v118, v108
	v_cvt_f32_f16_e32 v120, v109
	v_cvt_f32_f16_e32 v109, v126
	v_cvt_f32_f16_e32 v117, v127
	v_cvt_f32_f16_sdwa v119, v127 dst_sel:DWORD dst_unused:UNUSED_PAD src0_sel:WORD_1
	v_sub_f32_e32 v108, 1.0, v92
	v_sub_f32_e32 v116, 1.0, v111
	v_sub_f32_e32 v118, 1.0, v118
	ds_write_b64 v201, v[108:109]
	ds_write_b64 v202, v[116:117]
	ds_write_b64 v203, v[118:119]
	v_cvt_f16_f32_e32 v108, v166
	v_cvt_f32_f16_e32 v93, v174
	v_sub_f32_e32 v92, 1.0, v120
	ds_write_b64 v125, v[92:93]
	v_cvt_f16_f32_e32 v93, v105
	v_cvt_f16_f32_e32 v92, v104
	v_cvt_f16_f32_e32 v104, v106
	v_cvt_f32_f16_e32 v92, v92
	v_add_f32_e32 v73, v73, v213
	v_add_f32_e32 v72, v72, v212
	v_add_f32_e32 v76, v76, v216
	v_mul_f32_e32 v73, 0xbfb8aa3b, v73
	v_mul_f32_e32 v72, 0xbfb8aa3b, v72
	v_mul_f32_e32 v76, 0xbfb8aa3b, v76
	v_exp_f32_e32 v73, v73
	v_exp_f32_e32 v72, v72
	v_exp_f32_e32 v76, v76
	v_add_f32_e32 v74, v74, v214
	v_add_f32_e32 v73, 1.0, v73
	v_add_f32_e32 v72, 1.0, v72
	v_add_f32_e32 v76, 1.0, v76
	v_rcp_f32_e32 v73, v73
	v_rcp_f32_e32 v72, v72
	v_rcp_f32_e32 v76, v76
	v_mul_f32_e32 v74, 0xbfb8aa3b, v74
	v_mul_f32_e64 v73, v73, -v221
	v_add_f32_e32 v77, v77, v217
	v_mul_f32_e64 v72, v72, -v220
	v_mul_f32_e32 v81, v76, v149
	v_mul_f32_e32 v76, 0x3fb8aa3b, v73
	v_exp_f32_e32 v74, v74
	v_mul_f32_e32 v80, 0x3fb8aa3b, v72
	v_add_f32_e32 v72, v72, v72
	v_exp_f32_e32 v76, v76
	v_mul_f32_e32 v72, 0x3fb8aa3b, v72
	v_exp_f32_e32 v72, v72
	v_add_f32_e32 v73, v73, v73
	v_mul_f32_e32 v73, 0x3fb8aa3b, v73
	v_add_f32_e32 v74, 1.0, v74
	v_exp_f32_e32 v80, v80
	v_exp_f32_e32 v73, v73
	v_sub_f32_e32 v90, 1.0, v76
	v_rcp_f32_e32 v74, v74
	v_add_f32_e32 v76, v78, v218
	v_mul_f32_e32 v76, 0xbfb8aa3b, v76
	v_sub_f32_e32 v72, 1.0, v72
	v_exp_f32_e32 v76, v76
	v_max_f32_e32 v72, 0, v72
	v_sub_f32_e32 v109, 1.0, v80
	v_sqrt_f32_e32 v80, v72
	v_mul_f32_e32 v72, 0xbfb8aa3b, v77
	v_sub_f32_e32 v73, 1.0, v73
	v_mul_f32_e64 v77, v74, -v222
	v_max_f32_e32 v73, 0, v73
	v_mul_f32_e32 v74, 0x3fb8aa3b, v77
	v_exp_f32_e32 v78, v74
	v_sqrt_f32_e32 v74, v73
	v_add_f32_e32 v73, 1.0, v76
	v_add_f32_e32 v76, v77, v77
	v_add_f32_e32 v75, v75, v215
	v_mul_f32_e32 v76, 0x3fb8aa3b, v76
	v_mul_f32_e32 v75, 0xbfb8aa3b, v75
	v_exp_f32_e32 v76, v76
	v_exp_f32_e32 v77, v75
	v_sub_f32_e32 v111, 1.0, v78
	v_exp_f32_e32 v72, v72
	v_sub_f32_e32 v75, 1.0, v76
	v_add_f32_e32 v76, 1.0, v77
	v_rcp_f32_e32 v76, v76
	v_add_f32_e32 v77, v79, v219
	v_mul_f32_e32 v77, 0xbfb8aa3b, v77
	v_exp_f32_e32 v77, v77
	v_mul_f32_e64 v76, v76, -v223
	v_mul_f32_e32 v78, 0x3fb8aa3b, v76
	v_add_f32_e32 v76, v76, v76
	v_mul_f32_e32 v76, 0x3fb8aa3b, v76
	v_exp_f32_e32 v76, v76
	v_exp_f32_e32 v78, v78
	v_add_f32_e32 v77, 1.0, v77
	v_rcp_f32_e32 v77, v77
	v_add_f32_e32 v72, 1.0, v72
	v_rcp_f32_e32 v72, v72
	v_rcp_f32_e32 v73, v73
	v_max_f32_e32 v75, 0, v75
	v_sub_f32_e32 v76, 1.0, v76
	v_sqrt_f32_e32 v75, v75
	v_sub_f32_e32 v91, 1.0, v78
	v_max_f32_e32 v76, 0, v76
	v_sqrt_f32_e32 v78, v76
	v_mul_f32_e32 v79, v77, v148
	v_lshl_add_u64 v[86:87], s[18:19], 0, v[144:145]
	v_cvt_pk_f16_f32 v77, v111, v91
	v_cvt_pk_f16_f32 v76, v109, v90
	v_mov_b32_e32 v208, v76
	v_mov_b32_e32 v209, v77
	v_and_b32_e32 v76, 0xffff0000, v146
	v_lshlrev_b32_e32 v77, 16, v147
	v_pk_mul_f32 v[72:73], v[72:73], v[76:77]
	v_fma_mixlo_f16 v116, v81, v80, 0
	v_pk_mul_f32 v[72:73], v[72:73], v[74:75]
	v_fma_mixlo_f16 v118, v79, v78, 0
	v_cvt_pk_f16_f32 v117, v72, v73
	v_lshl_add_u64 v[84:85], s[16:17], 0, v[144:145]
	v_pack_b32_f16 v72, v116, v117
	v_alignbit_b32 v73, v118, v117, 16
	v_mov_b32_e32 v224, v72
	v_mov_b32_e32 v225, v73
	v_cvt_f32_f16_e32 v76, v108
	v_cvt_f32_f16_e32 v89, v107
	v_sub_f32_e32 v88, 1.0, v76
	v_lshlrev_b32_e32 v76, 8, v142
	v_and_b32_e32 v105, 0x2f00, v76
	v_add_u32_e32 v105, s26, v105
	v_add_u32_e32 v106, v105, v124
	ds_write_b64 v106, v[88:89]
	v_cvt_f32_f16_e32 v89, v113
	v_sub_f32_e32 v88, 1.0, v92
	v_cvt_f32_f16_e32 v92, v93
	v_add_u32_e32 v93, v105, v123
	ds_write_b64 v93, v[88:89]
	v_cvt_f32_f16_sdwa v89, v113 dst_sel:DWORD dst_unused:UNUSED_PAD src0_sel:WORD_1
	v_sub_f32_e32 v88, 1.0, v92
	v_cvt_f32_f16_e32 v92, v104
	v_add_u32_e32 v93, v105, v115
	ds_write_b64 v93, v[88:89]
	v_cvt_f32_f16_e32 v89, v112
	v_sub_f32_e32 v88, 1.0, v92
	v_cvt_f16_f32_e32 v92, v98
	v_add_u32_e32 v93, v105, v114
	ds_write_b64 v93, v[88:89]
	v_cvt_f16_f32_e32 v93, v96
	v_cvt_f32_f16_e32 v88, v92
	v_cvt_f32_f16_e32 v89, v110
	v_cvt_f16_f32_e32 v92, v94
	v_cvt_f16_f32_e32 v94, v95
	v_sub_f32_e32 v88, 1.0, v88
	v_cvt_f32_f16_e32 v93, v93
	v_add_u32_e32 v95, v105, v103
	ds_write_b64 v95, v[88:89]
	v_cvt_f32_f16_e32 v89, v99
	v_sub_f32_e32 v88, 1.0, v93
	v_cvt_f32_f16_e32 v92, v92
	v_add_u32_e32 v93, v105, v102
	ds_write_b64 v93, v[88:89]
	v_cvt_f32_f16_sdwa v89, v99 dst_sel:DWORD dst_unused:UNUSED_PAD src0_sel:WORD_1
	v_sub_f32_e32 v88, 1.0, v92
	v_add_u32_e32 v92, v105, v101
	v_cvt_f32_f16_e32 v93, v94
	ds_write_b64 v92, v[88:89]
	v_cvt_f32_f16_e32 v89, v97
	v_cvt_f16_f32_e32 v92, v109
	v_sub_f32_e32 v88, 1.0, v93
	v_add_u32_e32 v93, v105, v100
	ds_write_b64 v93, v[88:89]
	v_cvt_f32_f16_e32 v88, v92
	v_cvt_f16_f32_e32 v89, v90
	v_cvt_f16_f32_e32 v93, v91
	v_cvt_f32_f16_e32 v91, v116
	v_sub_f32_e32 v90, 1.0, v88
	v_lshlrev_b32_e32 v88, 8, v140
	v_and_b32_e32 v88, 0x3f00, v88
	v_add_u32_e32 v88, s26, v88
	v_cvt_f16_f32_e32 v92, v111
	v_cvt_f32_f16_e32 v89, v89
	v_add_u32_e32 v94, v88, v124
	ds_write_b64 v94, v[90:91]
	v_cvt_f32_f16_e32 v91, v117
	v_sub_f32_e32 v90, 1.0, v89
	v_add_u32_e32 v89, v88, v123
	v_cvt_f32_f16_e32 v92, v92
	ds_write_b64 v89, v[90:91]
	v_cvt_f32_f16_sdwa v91, v117 dst_sel:DWORD dst_unused:UNUSED_PAD src0_sel:WORD_1
	v_cvt_f32_f16_e32 v89, v93
	v_sub_f32_e32 v90, 1.0, v92
	v_add_u32_e32 v92, v88, v115
	ds_write_b64 v92, v[90:91]
	v_cvt_f32_f16_e32 v91, v118
	v_sub_f32_e32 v90, 1.0, v89
	v_add_u32_e32 v89, v88, v114
	ds_write_b64 v89, v[90:91]
	v_and_b32_e32 v89, 0xffff0000, v139
	v_add_f32_e32 v68, v68, v230
	v_mul_f32_e32 v68, 0xbfb8aa3b, v68
	v_exp_f32_e32 v68, v68
	v_add_f32_e32 v64, v64, v234
	v_mul_f32_e32 v64, 0xbfb8aa3b, v64
	v_exp_f32_e32 v64, v64
	v_add_f32_e32 v68, 1.0, v68
	v_rcp_f32_e32 v68, v68
	v_add_f32_e32 v65, v65, v235
	v_add_f32_e32 v64, 1.0, v64
	v_mul_f32_e32 v65, 0xbfb8aa3b, v65
	v_mul_f32_e64 v68, v68, -v244
	v_mul_f32_e32 v76, 0x3fb8aa3b, v68
	v_add_f32_e32 v68, v68, v68
	v_mul_f32_e32 v68, 0x3fb8aa3b, v68
	v_exp_f32_e32 v68, v68
	v_rcp_f32_e32 v64, v64
	v_exp_f32_e32 v65, v65
	v_lshlrev_b32_e32 v72, 16, v138
	v_sub_f32_e32 v68, 1.0, v68
	v_max_f32_e32 v68, 0, v68
	v_sqrt_f32_e32 v80, v68
	v_add_f32_e32 v68, v69, v231
	v_mul_f32_e32 v68, 0xbfb8aa3b, v68
	v_exp_f32_e32 v68, v68
	v_mul_f32_e32 v72, v64, v72
	v_add_f32_e32 v64, 1.0, v65
	v_add_f32_e32 v69, v70, v232
	v_add_f32_e32 v68, 1.0, v68
	v_rcp_f32_e32 v68, v68
	v_mul_f32_e32 v69, 0xbfb8aa3b, v69
	v_exp_f32_e32 v69, v69
	v_add_f32_e32 v71, v71, v233
	v_mul_f32_e64 v65, v68, -v245
	v_mul_f32_e32 v68, 0x3fb8aa3b, v65
	v_exp_f32_e32 v68, v68
	v_mul_f32_e32 v71, 0xbfb8aa3b, v71
	v_exp_f32_e32 v71, v71
	v_add_f32_e32 v65, v65, v65
	v_sub_f32_e32 v70, 1.0, v68
	v_add_f32_e32 v68, 1.0, v69
	v_rcp_f32_e32 v68, v68
	v_mul_f32_e32 v65, 0x3fb8aa3b, v65
	v_exp_f32_e32 v65, v65
	v_add_f32_e32 v66, v66, v236
	v_mul_f32_e64 v69, v68, -v246
	v_add_f32_e32 v71, 1.0, v71
	v_mul_f32_e32 v66, 0xbfb8aa3b, v66
	v_mul_f32_e32 v68, 0x3fb8aa3b, v69
	v_rcp_f32_e32 v71, v71
	v_exp_f32_e32 v66, v66
	v_exp_f32_e32 v73, v68
	v_add_f32_e32 v67, v67, v237
	v_sub_f32_e32 v65, 1.0, v65
	v_mul_f32_e32 v67, 0xbfb8aa3b, v67
	v_max_f32_e32 v65, 0, v65
	v_add_f32_e32 v69, v69, v69
	v_exp_f32_e32 v67, v67
	v_mul_f32_e64 v71, v71, -v247
	v_sqrt_f32_e32 v68, v65
	v_add_f32_e32 v65, 1.0, v66
	v_sub_f32_e32 v66, 1.0, v73
	v_mul_f32_e32 v69, 0x3fb8aa3b, v69
	v_mul_f32_e32 v73, 0x3fb8aa3b, v71
	v_add_f32_e32 v71, v71, v71
	v_exp_f32_e32 v69, v69
	v_mul_f32_e32 v71, 0x3fb8aa3b, v71
	v_exp_f32_e32 v71, v71
	v_exp_f32_e32 v76, v76
	v_exp_f32_e32 v73, v73
	v_add_f32_e32 v67, 1.0, v67
	v_rcp_f32_e32 v67, v67
	v_sub_f32_e32 v69, 1.0, v69
	v_rcp_f32_e32 v64, v64
	v_rcp_f32_e32 v65, v65
	v_max_f32_e32 v69, 0, v69
	v_sub_f32_e32 v71, 1.0, v71
	v_sub_f32_e32 v76, 1.0, v76
	v_sqrt_f32_e32 v69, v69
	v_sub_f32_e32 v73, 1.0, v73
	v_max_f32_e32 v71, 0, v71
	v_sqrt_f32_e32 v71, v71
	v_mul_f32_e32 v74, v67, v89
	v_cvt_f16_f32_e32 v78, v66
	v_cvt_pk_f16_f32 v67, v66, v73
	v_cvt_pk_f16_f32 v66, v76, v70
	v_cvt_f16_f32_e32 v75, v76
	v_mov_b32_e32 v210, v66
	v_mov_b32_e32 v211, v67
	v_add_u32_e32 v86, v160, v86
	s_nop 0
	v_permlane16_swap_b32 v208, v210
	v_permlane16_swap_b32 v209, v211
	global_store_dwordx4 v[86:87], v[208:211], off
	v_and_b32_e32 v66, 0xffff0000, v138
	v_lshlrev_b32_e32 v67, 16, v139
	v_pk_mul_f32 v[64:65], v[64:65], v[66:67]
	v_cvt_f16_f32_e32 v77, v70
	v_pk_mul_f32 v[64:65], v[64:65], v[68:69]
	v_fma_mixlo_f16 v70, v72, v80, 0
	v_cvt_pk_f16_f32 v66, v64, v65
	v_fma_mixlo_f16 v67, v74, v71, 0
	v_pack_b32_f16 v64, v70, v66
	v_cvt_f32_f16_e32 v68, v75
	v_alignbit_b32 v65, v67, v66, 16
	v_add_u32_e32 v84, v160, v84
	s_nop 1
	v_mov_b32_e32 v208, v224
	v_mov_b32_e32 v209, v225
	v_mov_b32_e32 v210, v64
	v_mov_b32_e32 v211, v65
	s_nop 1
	v_permlane16_swap_b32 v208, v210
	v_permlane16_swap_b32 v209, v211
	global_store_dwordx4 v[84:85], v[208:211], off
	v_cvt_f32_f16_e32 v65, v70
	v_sub_f32_e32 v64, 1.0, v68
	v_add_u32_e32 v68, v88, v103
	v_cvt_f32_f16_e32 v69, v77
	v_cvt_f16_f32_e32 v79, v73
	ds_write_b64 v68, v[64:65]
	v_cvt_f32_f16_e32 v65, v66
	v_cvt_f32_f16_e32 v68, v78
	v_sub_f32_e32 v64, 1.0, v69
	v_add_u32_e32 v69, v88, v102
	ds_write_b64 v69, v[64:65]
	v_cvt_f32_f16_sdwa v65, v66 dst_sel:DWORD dst_unused:UNUSED_PAD src0_sel:WORD_1
	v_cvt_f32_f16_e32 v66, v79
	v_cvt_f32_f16_e32 v67, v67
	v_sub_f32_e32 v64, 1.0, v68
	v_add_u32_e32 v68, v88, v101
	ds_write_b64 v68, v[64:65]
	v_sub_f32_e32 v66, 1.0, v66
	v_add_u32_e32 v64, v88, v100
	ds_write_b64 v64, v[66:67]
	s_waitcnt lgkmcnt(0)
	s_and_saveexec_b64 s[2:3], s[4:5]
	s_cbranch_execz .LBB0_1222
	s_ashr_i32 s10, s31, 6
	s_mov_b32 s11, 0
	v_mov_b32_e32 v65, 0
	v_mov_b32_e32 v66, 1.0
	s_mov_b32 s12, 48
